# v050 + tile-index division by the group height (always 8) in the four GEMM unit headers folded to a shift and a mask (hipcc's v_rcp_iflag / v_readfirstlane reciprocal chain removed, 108 instructions)
# speedup vs baseline: 1.0009x; 1.0006x over previous
.LBB0_267:
	s_add_i32 s51, s51, 1
	v_readlane_b32 s1, v254, 48
	s_mul_i32 s1, s51, s1
	s_mul_hi_u32 s2, s51, s84
	s_add_i32 s2, s2, s1
	s_mul_i32 s1, s51, s84
	s_add_u32 s26, s1, s75
	v_readlane_b32 s1, v254, 47
	s_addc_u32 s27, s2, s1
	v_mov_b64_e32 v[2:3], 0x900
	v_cmp_lt_i64_e64 s[6:7], s[26:27], v[2:3]
	v_mov_b64_e32 v[2:3], 0x8ff
	v_cmp_gt_i64_e32 vcc, s[26:27], v[2:3]
	s_cbranch_vccnz .LBB0_269
	s_ashr_i32 s1, s26, 31
	s_lshr_b32 s1, s1, 29
	s_add_i32 s1, s26, s1
	s_ashr_i32 s2, s1, 3
	s_and_b32 s1, s1, -8
	s_sub_i32 s1, s26, s1
	s_cmp_lt_i32 s1, 0
	s_cselect_b32 s22, s12, 0x120
	s_mul_i32 s1, s1, s22
	s_add_i32 s1, s1, s2
	s_mul_hi_i32 s2, s1, 0x38e38e39
	s_lshr_b32 s22, s2, 31
	s_ashr_i32 s2, s2, 5
	s_add_i32 s2, s2, s22
	s_lshl_b32 s23, s2, 3
	s_sub_i32 s22, 0x80, s23
	s_min_i32 s24, s22, 8
	s_mulk_i32 s2, 0x90
	s_sub_i32 s1, s1, s2
	s_lshr_b32 s22, s1, 3
	s_and_b32 s1, s1, 7
	s_add_i32 s24, s23, s1

.LBB0_615:
	s_ashr_i32 s21, s21, 3
	s_add_i32 s21, s26, s21
	s_ashr_i32 s23, s21, 31
	s_lshr_b32 s23, s23, 26
	s_add_i32 s23, s21, s23
	s_ashr_i32 s24, s23, 6
	s_lshl_b32 s25, s24, 3
	s_sub_i32 s24, 0x80, s25
	s_min_i32 s26, s24, 8
	s_andn2_b32 s23, s23, 63
	s_sub_i32 s21, s21, s23
	s_lshr_b32 s24, s21, 3
	s_and_b32 s21, s21, 7
	s_add_i32 s26, s25, s21

.LBB0_740:
	s_add_i32 s62, s62, 1
	v_readlane_b32 s12, v255, 24
	s_mul_i32 s10, s62, s59
	s_mul_hi_u32 s11, s62, s12
	s_add_i32 s11, s11, s10
	s_mul_i32 s10, s62, s12
	v_readlane_b32 s12, v255, 28
	s_add_u32 s12, s10, s12
	s_addc_u32 s13, s11, s58
	v_mov_b64_e32 v[2:3], 0x1600
	v_cmp_lt_i64_e64 s[10:11], s[12:13], v[2:3]
	v_mov_b64_e32 v[2:3], 0x15ff
	v_cmp_gt_i64_e32 vcc, s[12:13], v[2:3]
	s_cbranch_vccnz .LBB0_742
	s_ashr_i32 s13, s12, 31
	s_lshr_b32 s13, s13, 29
	s_add_i32 s13, s12, s13
	s_ashr_i32 s28, s13, 3
	s_and_b32 s13, s13, -8
	s_sub_i32 s12, s12, s13
	s_cmp_lt_i32 s12, 0
	s_movk_i32 s13, 0x2c1
	s_cselect_b32 s13, s13, 0x2c0
	s_mul_i32 s12, s12, s13
	s_add_i32 s12, s12, s28
	s_mul_hi_i32 s13, s12, 0x2e8ba2e9
	s_lshr_b32 s28, s13, 31
	s_ashr_i32 s13, s13, 6
	s_add_i32 s13, s13, s28
	s_lshl_b32 s29, s13, 3
	s_sub_i32 s28, 0x80, s29
	s_min_i32 s30, s28, 8
	s_mulk_i32 s13, 0x160
	s_sub_i32 s12, s12, s13
	s_lshr_b32 s28, s12, 3
	s_and_b32 s12, s12, 7
	s_add_i32 s30, s29, s12

.LBB0_899:
	s_ashr_i32 s6, s19, 3
	s_add_i32 s6, s22, s6
	s_ashr_i32 s7, s6, 31
	s_lshr_b32 s7, s7, 26
	s_add_i32 s7, s6, s7
	s_ashr_i32 s19, s7, 6
	s_lshl_b32 s19, s19, 3
	s_sub_i32 s21, 0x80, s19
	s_min_i32 s21, s21, 8
	s_andn2_b32 s7, s7, 63
	s_sub_i32 s6, s6, s7
	s_lshr_b32 s56, s6, 3
	s_and_b32 s6, s6, 7
	s_add_i32 s57, s19, s6
